# SSD G stage: acum/dt quads of each 16-column block fetched one block ahead
# baseline (speedup 1.0000x reference)
; __device__ __forceinline__ unsigned cvt_pk(float lo, float hi) { f32x2 v = {lo, hi}; bf16x2_t b = __builtin_convertvector(v, bf16x2_t); return __builtin_bit_cast(unsigned, b); }
; __device__ __forceinline__ u32x2 pack4(f32x4 v) { u32x2 r; r.x = cvt_pk(v[0], v[1]); r.y = cvt_pk(v[2], v[3]); return r; }
; __device__ __forceinline__ float bflo(unsigned w) { return __uint_as_float(w << 16); }
; __device__ __forceinline__ float bfhi(unsigned w) { return __uint_as_float(w & 0xffff0000u); }
; __device__ __forceinline__ void ssd_prompt_item(const Params& p, int item, const int wv) {
;     ...
;     const float alast = acum_l[127];
; #pragma unroll
;     for (int r2 = 0; r2 < 2; ++r2) {
;       int pp = (tid >> 4) + 32 * r2, jc = tid & 15;
;       u32x4 xv = *(const u32x4*)(xT_l + pp * 136 + jc * 8);
;       float wj[8];
; #pragma unroll
;       for (int e = 0; e < 8; ++e) wj[e] = dt_l[jc * 8 + e] * __expf(alast - acum_l[jc * 8 + e]);
;       u32x4 ov;
;       ov.x = cvt_pk(bflo(xv.x) * wj[0], bfhi(xv.x) * wj[1]); ov.y = cvt_pk(bflo(xv.y) * wj[2], bfhi(xv.y) * wj[3]);
;       ov.z = cvt_pk(bflo(xv.z) * wj[4], bfhi(xv.z) * wj[5]); ov.w = cvt_pk(bflo(xv.w) * wj[6], bfhi(xv.w) * wj[7]);
;       *(u32x4*)(xw_l + pp * 136 + jc * 8) = ov;
;     }
;     __syncthreads();
;     {
;       const int i = wid * 16 + fr;
;       const float ai = acum_l[i];
; #pragma unroll
;       for (int jb = 0; jb < 8; ++jb) {
;         f32x4 gv = {0.f, 0.f, 0.f, 0.f};
;         if (jb <= wid) {
;           f32x4 aj = *(const f32x4*)(acum_l + jb * 16 + fq * 4);
;           f32x4 dj = *(const f32x4*)(dt_l + jb * 16 + fq * 4);
; #pragma unroll
;           for (int e = 0; e < 4; ++e) { int j = jb * 16 + fq * 4 + e; gv[e] = (j <= i) ? cb[jb][e] * __expf(ai - aj[e]) * dj[e] : 0.f; }
;         }
;         *(u32x2*)(G_l + i * 136 + jb * 16 + fq * 4) = pack4(gv);
;       }
;     }
.LBB0_593:
	v_mov_b32_e32 v128, s39
	ds_read_b32 v227, v128
	ds_read_b128 v[228:231], v213
	ds_read_b128 v[232:235], v215
	ds_read_b128 v[32:35], v211
	ds_read_b128 v[36:39], v214
	ds_read_b128 v[128:131], v212
	ds_read_b128 v[150:153], v212 offset:8704
	s_mov_b32 s41, 0x5040100
	s_and_b64 vcc, exec, s[96:97]
	s_waitcnt lgkmcnt(5)
	v_sub_f32_e32 v154, v227, v228
	v_sub_f32_e32 v155, v227, v229
	v_sub_f32_e32 v156, v227, v230
	v_sub_f32_e32 v157, v227, v231
	v_mul_f32_e32 v154, 0x3fb8aa3b, v154
	v_mul_f32_e32 v155, 0x3fb8aa3b, v155
	v_mul_f32_e32 v156, 0x3fb8aa3b, v156
	v_mul_f32_e32 v157, 0x3fb8aa3b, v157
	v_exp_f32_e32 v154, v154
	v_exp_f32_e32 v155, v155
	v_exp_f32_e32 v156, v156
	v_exp_f32_e32 v157, v157
	s_waitcnt lgkmcnt(4)
	v_sub_f32_e32 v162, v227, v232
	v_sub_f32_e32 v163, v227, v233
	v_sub_f32_e32 v164, v227, v234
	v_sub_f32_e32 v165, v227, v235
	v_mul_f32_e32 v162, 0x3fb8aa3b, v162
	v_mul_f32_e32 v163, 0x3fb8aa3b, v163
	v_mul_f32_e32 v164, 0x3fb8aa3b, v164
	v_mul_f32_e32 v165, 0x3fb8aa3b, v165
	v_exp_f32_e32 v162, v162
	v_exp_f32_e32 v163, v163
	v_exp_f32_e32 v164, v164
	v_exp_f32_e32 v165, v165
	s_waitcnt lgkmcnt(3)
	v_pk_mul_f32 v[154:155], v[32:33], v[154:155]
	v_pk_mul_f32 v[156:157], v[34:35], v[156:157]
	s_waitcnt lgkmcnt(2)
	v_pk_mul_f32 v[162:163], v[36:37], v[162:163]
	v_pk_mul_f32 v[164:165], v[38:39], v[164:165]
	s_waitcnt lgkmcnt(1)
	v_lshlrev_b32_e32 v170, 16, v128
	v_and_b32_e32 v171, 0xffff0000, v128
	v_lshlrev_b32_e32 v172, 16, v129
	v_and_b32_e32 v173, 0xffff0000, v129
	v_lshlrev_b32_e32 v236, 16, v130
	v_and_b32_e32 v237, 0xffff0000, v130
	v_lshlrev_b32_e32 v238, 16, v131
	v_and_b32_e32 v239, 0xffff0000, v131
	v_pk_mul_f32 v[170:171], v[154:155], v[170:171]
	v_pk_mul_f32 v[172:173], v[156:157], v[172:173]
	v_pk_mul_f32 v[236:237], v[162:163], v[236:237]
	v_pk_mul_f32 v[238:239], v[164:165], v[238:239]
	v_cvt_pk_bf16_f32 v128, v170, v171
	v_cvt_pk_bf16_f32 v129, v172, v173
	v_cvt_pk_bf16_f32 v130, v236, v237
	v_cvt_pk_bf16_f32 v131, v238, v239
	ds_write_b128 v216, v[128:131]
	s_waitcnt lgkmcnt(1)
	v_lshlrev_b32_e32 v170, 16, v150
	v_and_b32_e32 v171, 0xffff0000, v150
	v_lshlrev_b32_e32 v172, 16, v151
	v_and_b32_e32 v173, 0xffff0000, v151
	v_lshlrev_b32_e32 v236, 16, v152
	v_and_b32_e32 v237, 0xffff0000, v152
	v_lshlrev_b32_e32 v238, 16, v153
	v_and_b32_e32 v239, 0xffff0000, v153
	v_pk_mul_f32 v[170:171], v[154:155], v[170:171]
	v_pk_mul_f32 v[172:173], v[156:157], v[172:173]
	v_pk_mul_f32 v[236:237], v[162:163], v[236:237]
	v_pk_mul_f32 v[238:239], v[164:165], v[238:239]
	v_cvt_pk_bf16_f32 v150, v170, v171
	v_cvt_pk_bf16_f32 v151, v172, v173
	v_cvt_pk_bf16_f32 v152, v236, v237
	v_cvt_pk_bf16_f32 v153, v238, v239
	ds_write_b128 v216, v[150:153] offset:8704
	s_waitcnt lgkmcnt(0)
	s_barrier
	ds_read_b32 v128, v197
	ds_read_b128 v[228:231], v198
	ds_read_b128 v[232:235], v199
	ds_read_b128 v[150:153], v198 offset:64
	ds_read_b128 v[154:157], v199 offset:64
	s_waitcnt lgkmcnt(3)
	v_sub_f32_e32 v129, v128, v228
	v_mul_f32_e32 v129, 0x3fb8aa3b, v129
	v_exp_f32_e32 v129, v129
	s_nop 0
	v_mul_f32_e32 v124, v124, v129
	s_waitcnt lgkmcnt(2)
	v_mul_f32_e32 v124, v232, v124
	v_cndmask_b32_e64 v130, v124, 0, s[18:19]
	v_sub_f32_e32 v124, v128, v229
	v_mul_f32_e32 v124, 0x3fb8aa3b, v124
	v_exp_f32_e32 v124, v124
	v_mov_b32_e32 v129, 0
	v_mul_f32_e32 v124, v125, v124
	v_mul_f32_e32 v124, v233, v124
	v_cndmask_b32_e64 v131, 0, v124, s[20:21]
	v_sub_f32_e32 v124, v128, v230
	v_sub_f32_e32 v125, v128, v231
	v_mul_f32_e32 v124, 0x3fb8aa3b, v124
	v_mul_f32_e32 v125, 0x3fb8aa3b, v125
	v_exp_f32_e32 v124, v124
	v_exp_f32_e32 v125, v125
	s_nop 0
	v_pk_mul_f32 v[124:125], v[126:127], v[124:125]
	s_nop 0
	v_pk_mul_f32 v[124:125], v[234:235], v[124:125]
	v_cvt_pk_bf16_f32 v126, v130, v131
	v_cvt_pk_bf16_f32 v124, v124, v125
	v_cndmask_b32_e64 v125, v124, 0, s[24:25]
	v_lshrrev_b32_e32 v124, 16, v124
	v_cndmask_b32_e64 v124, v124, 0, s[22:23]
	v_perm_b32 v127, v124, v125, s41
	v_add_u32_e32 v124, v195, v194
	ds_write_b64 v124, v[126:127] offset:34816
	v_mov_b32_e32 v125, 0
	v_mov_b32_e32 v126, 0
	v_mov_b32_e32 v127, 0
	v_mov_b32_e32 v130, 0
	s_cbranch_vccnz .LBB0_595
	ds_read_b128 v[32:35], v198 offset:128
	ds_read_b128 v[36:39], v199 offset:128
	v_readlane_b32 s96, v250, 45
	v_readlane_b32 s97, v250, 46
	s_waitcnt lgkmcnt(4)
	v_sub_f32_e32 v125, v128, v150
	v_sub_f32_e32 v126, v128, v151
	v_mul_f32_e32 v125, 0x3fb8aa3b, v125
	v_mul_f32_e32 v127, 0x3fb8aa3b, v126
	v_exp_f32_e32 v126, v125
	v_exp_f32_e32 v127, v127
	v_sub_f32_e32 v125, v128, v152
	v_mul_f32_e32 v125, 0x3fb8aa3b, v125
	v_exp_f32_e32 v130, v125
	v_sub_f32_e32 v125, v128, v153
	v_mul_f32_e32 v125, 0x3fb8aa3b, v125
	v_exp_f32_e32 v131, v125
	v_pk_mul_f32 v[120:121], v[120:121], v[126:127]
	v_pk_mul_f32 v[122:123], v[122:123], v[130:131]
	s_waitcnt lgkmcnt(3)
	v_pk_mul_f32 v[120:121], v[154:155], v[120:121]
	v_pk_mul_f32 v[122:123], v[156:157], v[122:123]
	v_cndmask_b32_e64 v125, v120, 0, s[96:97]
	v_readlane_b32 s96, v250, 43
	v_readlane_b32 s97, v250, 44
	s_nop 1
	v_cndmask_b32_e64 v126, v121, 0, s[96:97]
	v_readlane_b32 s96, v250, 41
	v_readlane_b32 s97, v250, 42
	s_nop 1
	v_cndmask_b32_e64 v127, v122, 0, s[96:97]
	v_readlane_b32 s96, v250, 39
	v_readlane_b32 s97, v250, 40
	s_nop 1
	v_cndmask_b32_e64 v130, v123, 0, s[96:97]
; __device__ __forceinline__ u32x2 pack4(f32x4 v) { u32x2 r; r.x = cvt_pk(v[0], v[1]); r.y = cvt_pk(v[2], v[3]); return r; }
; __device__ __forceinline__ void ssd_prompt_item(const Params& p, int item, const int wv) {
;     ...
;       for (int jb = 0; jb < 8; ++jb) {
;         f32x4 gv = {0.f, 0.f, 0.f, 0.f};
;         if (jb <= wid) {
;           f32x4 aj = *(const f32x4*)(acum_l + jb * 16 + fq * 4);
;           f32x4 dj = *(const f32x4*)(dt_l + jb * 16 + fq * 4);
; #pragma unroll
;           for (int e = 0; e < 4; ++e) { int j = jb * 16 + fq * 4 + e; gv[e] = (j <= i) ? cb[jb][e] * __expf(ai - aj[e]) * dj[e] : 0.f; }
;         }
;         *(u32x2*)(G_l + i * 136 + jb * 16 + fq * 4) = pack4(gv);
.LBB0_595:
	v_cvt_pk_bf16_f32 v120, v125, v126
	v_cvt_pk_bf16_f32 v121, v127, v130
	ds_write_b64 v124, v[120:121] offset:34848
	s_and_b64 vcc, exec, s[84:85]
	v_mov_b32_e32 v120, 0
	v_mov_b32_e32 v121, 0
	v_mov_b32_e32 v122, 0
	s_cbranch_vccnz .LBB0_597
	ds_read_b128 v[150:153], v198 offset:192
	ds_read_b128 v[154:157], v199 offset:192
	v_readlane_b32 s96, v250, 51
	v_readlane_b32 s97, v250, 52
	s_waitcnt lgkmcnt(4)
	v_sub_f32_e32 v120, v128, v32
	v_sub_f32_e32 v121, v128, v33
	v_mul_f32_e32 v120, 0x3fb8aa3b, v120
	v_mul_f32_e32 v121, 0x3fb8aa3b, v121
	v_exp_f32_e32 v120, v120
	v_exp_f32_e32 v121, v121
	v_sub_f32_e32 v122, v128, v34
	v_sub_f32_e32 v123, v128, v35
	v_mul_f32_e32 v122, 0x3fb8aa3b, v122
	v_mul_f32_e32 v123, 0x3fb8aa3b, v123
	v_exp_f32_e32 v122, v122
	v_exp_f32_e32 v123, v123
	v_pk_mul_f32 v[116:117], v[116:117], v[120:121]
	v_pk_mul_f32 v[118:119], v[118:119], v[122:123]
	s_waitcnt lgkmcnt(3)
	v_pk_mul_f32 v[116:117], v[36:37], v[116:117]
	v_pk_mul_f32 v[118:119], v[38:39], v[118:119]
	v_cndmask_b32_e64 v120, v117, 0, s[96:97]
	v_readlane_b32 s96, v250, 49
	v_readlane_b32 s97, v250, 50
	v_cndmask_b32_e64 v129, v116, 0, s[42:43]
	s_nop 0
	v_cndmask_b32_e64 v121, v118, 0, s[96:97]
	v_readlane_b32 s96, v250, 47
	v_readlane_b32 s97, v250, 48
	s_nop 1
	v_cndmask_b32_e64 v122, v119, 0, s[96:97]
.LBB0_597:
	v_cvt_pk_bf16_f32 v116, v129, v120
	v_cvt_pk_bf16_f32 v117, v121, v122
	ds_write_b64 v124, v[116:117] offset:34880
	v_mov_b32_e32 v116, 0
	s_and_b64 vcc, exec, s[94:95]
	v_mov_b32_e32 v117, 0
	v_mov_b32_e32 v118, 0
	v_mov_b32_e32 v119, 0
	v_mov_b32_e32 v120, 0
	s_cbranch_vccnz .LBB0_599
	ds_read_b128 v[32:35], v198 offset:256
	ds_read_b128 v[36:39], v199 offset:256
	s_waitcnt lgkmcnt(4)
	v_sub_f32_e32 v117, v128, v150
	v_sub_f32_e32 v118, v128, v151
	v_mul_f32_e32 v117, 0x3fb8aa3b, v117
	v_mul_f32_e32 v119, 0x3fb8aa3b, v118
	v_exp_f32_e32 v118, v117
	v_sub_f32_e32 v117, v128, v152
	v_mul_f32_e32 v117, 0x3fb8aa3b, v117
	v_exp_f32_e32 v120, v117
	v_sub_f32_e32 v117, v128, v153
	v_mul_f32_e32 v117, 0x3fb8aa3b, v117
	v_exp_f32_e32 v119, v119
	v_exp_f32_e32 v121, v117
	v_pk_mul_f32 v[96:97], v[96:97], v[118:119]
	v_pk_mul_f32 v[98:99], v[98:99], v[120:121]
	s_waitcnt lgkmcnt(3)
	v_pk_mul_f32 v[96:97], v[154:155], v[96:97]
	v_pk_mul_f32 v[98:99], v[156:157], v[98:99]
	v_cndmask_b32_e64 v117, v96, 0, s[10:11]
	v_cndmask_b32_e64 v118, v97, 0, s[8:9]
	v_cndmask_b32_e64 v119, v98, 0, s[6:7]
	v_cndmask_b32_e64 v120, v99, 0, s[44:45]
.LBB0_599:
	v_cvt_pk_bf16_f32 v96, v117, v118
	v_cvt_pk_bf16_f32 v97, v119, v120
	ds_write_b64 v124, v[96:97] offset:34912
	s_and_b64 vcc, exec, s[86:87]
	v_mov_b32_e32 v96, 0
	v_mov_b32_e32 v97, 0
	v_mov_b32_e32 v98, 0
	s_cbranch_vccnz .LBB0_601
	ds_read_b128 v[150:153], v198 offset:320
	ds_read_b128 v[154:157], v199 offset:320
	s_waitcnt lgkmcnt(4)
	v_sub_f32_e32 v96, v128, v32
	v_sub_f32_e32 v97, v128, v33
	v_sub_f32_e32 v98, v128, v34
	v_sub_f32_e32 v99, v128, v35
	v_mul_f32_e32 v96, 0x3fb8aa3b, v96
	v_mul_f32_e32 v97, 0x3fb8aa3b, v97
	v_mul_f32_e32 v98, 0x3fb8aa3b, v98
	v_mul_f32_e32 v99, 0x3fb8aa3b, v99
	v_exp_f32_e32 v96, v96
	v_exp_f32_e32 v97, v97
	v_exp_f32_e32 v98, v98
	v_exp_f32_e32 v99, v99
	v_pk_mul_f32 v[96:97], v[112:113], v[96:97]
	s_waitcnt lgkmcnt(3)
	v_pk_mul_f32 v[96:97], v[36:37], v[96:97]
	v_pk_mul_f32 v[98:99], v[114:115], v[98:99]
	v_cndmask_b32_e64 v116, v96, 0, s[58:59]
	v_pk_mul_f32 v[98:99], v[38:39], v[98:99]
	v_cndmask_b32_e64 v96, v97, 0, s[56:57]
	v_cndmask_b32_e64 v97, v98, 0, s[54:55]
	v_cndmask_b32_e64 v98, v99, 0, s[52:53]
.LBB0_601:
	v_cvt_pk_bf16_f32 v96, v116, v96
	v_cvt_pk_bf16_f32 v97, v97, v98
	ds_write_b64 v124, v[96:97] offset:34944
	v_mov_b32_e32 v96, 0
	s_and_b64 vcc, exec, s[92:93]
	v_mov_b32_e32 v97, 0
	v_mov_b32_e32 v98, 0
	v_mov_b32_e32 v99, 0
	v_mov_b32_e32 v112, 0
	s_cbranch_vccnz .LBB0_603
	ds_read_b128 v[32:35], v198 offset:384
	ds_read_b128 v[36:39], v199 offset:384
	s_waitcnt lgkmcnt(4)
	v_sub_f32_e32 v97, v128, v150
	v_sub_f32_e32 v98, v128, v151
	v_mul_f32_e32 v97, 0x3fb8aa3b, v97
	v_mul_f32_e32 v99, 0x3fb8aa3b, v98
	v_exp_f32_e32 v98, v97
	v_sub_f32_e32 v97, v128, v152
	v_mul_f32_e32 v97, 0x3fb8aa3b, v97
	v_exp_f32_e32 v112, v97
	v_sub_f32_e32 v97, v128, v153
	v_mul_f32_e32 v97, 0x3fb8aa3b, v97
	v_exp_f32_e32 v99, v99
	v_exp_f32_e32 v113, v97
	v_pk_mul_f32 v[98:99], v[104:105], v[98:99]
	v_pk_mul_f32 v[104:105], v[106:107], v[112:113]
	s_waitcnt lgkmcnt(3)
	v_pk_mul_f32 v[98:99], v[154:155], v[98:99]
	v_pk_mul_f32 v[104:105], v[156:157], v[104:105]
	v_cndmask_b32_e64 v97, v98, 0, s[66:67]
	v_cndmask_b32_e64 v98, v99, 0, s[64:65]
	v_cndmask_b32_e64 v99, v104, 0, s[62:63]
	v_cndmask_b32_e64 v112, v105, 0, s[60:61]
.LBB0_603:
	v_cvt_pk_bf16_f32 v98, v97, v98
	v_cvt_pk_bf16_f32 v99, v99, v112
	ds_write_b64 v124, v[98:99] offset:34976
	s_and_b64 vcc, exec, s[88:89]
	v_mov_b32_e32 v97, 0
	v_mov_b32_e32 v98, 0
	v_mov_b32_e32 v99, 0
	s_cbranch_vccnz .LBB0_605
	ds_read_b128 v[150:153], v198 offset:448
	ds_read_b128 v[154:157], v199 offset:448
	s_waitcnt lgkmcnt(4)
	v_sub_f32_e32 v96, v128, v32
	v_sub_f32_e32 v97, v128, v33
	v_sub_f32_e32 v98, v128, v34
	v_sub_f32_e32 v99, v128, v35
	v_mul_f32_e32 v96, 0x3fb8aa3b, v96
	v_mul_f32_e32 v97, 0x3fb8aa3b, v97
	v_mul_f32_e32 v98, 0x3fb8aa3b, v98
	v_mul_f32_e32 v99, 0x3fb8aa3b, v99
	v_exp_f32_e32 v96, v96
	v_exp_f32_e32 v97, v97
	v_exp_f32_e32 v98, v98
	v_exp_f32_e32 v99, v99
	v_pk_mul_f32 v[96:97], v[108:109], v[96:97]
	s_waitcnt lgkmcnt(3)
	v_pk_mul_f32 v[96:97], v[36:37], v[96:97]
	v_pk_mul_f32 v[98:99], v[110:111], v[98:99]
	v_cndmask_b32_e64 v96, v96, 0, s[74:75]
	v_pk_mul_f32 v[98:99], v[38:39], v[98:99]
	v_cndmask_b32_e64 v97, v97, 0, s[72:73]
	v_cndmask_b32_e64 v98, v98, 0, s[70:71]
	v_cndmask_b32_e64 v99, v99, 0, s[68:69]
.LBB0_605:
	v_cvt_pk_bf16_f32 v96, v96, v97
	v_cvt_pk_bf16_f32 v97, v98, v99
	ds_write_b64 v124, v[96:97] offset:35008
	v_mov_b32_e32 v96, 0
	s_and_b64 vcc, exec, s[90:91]
	v_mov_b32_e32 v97, 0
	v_mov_b32_e32 v98, 0
	v_mov_b32_e32 v99, 0
	s_cbranch_vccnz .LBB0_607
	s_waitcnt lgkmcnt(2)
	v_sub_f32_e32 v96, v128, v150
	v_sub_f32_e32 v97, v128, v151
	v_sub_f32_e32 v98, v128, v152
	v_sub_f32_e32 v99, v128, v153
	v_mul_f32_e32 v96, 0x3fb8aa3b, v96
	v_mul_f32_e32 v97, 0x3fb8aa3b, v97
	v_mul_f32_e32 v98, 0x3fb8aa3b, v98
	v_mul_f32_e32 v99, 0x3fb8aa3b, v99
	v_exp_f32_e32 v96, v96
	v_exp_f32_e32 v97, v97
	v_exp_f32_e32 v98, v98
	v_exp_f32_e32 v99, v99
	v_pk_mul_f32 v[96:97], v[100:101], v[96:97]
	s_waitcnt lgkmcnt(1)
	v_pk_mul_f32 v[96:97], v[154:155], v[96:97]
	v_pk_mul_f32 v[98:99], v[102:103], v[98:99]
	v_cndmask_b32_e64 v96, v96, 0, s[82:83]
	v_pk_mul_f32 v[98:99], v[156:157], v[98:99]
	v_cndmask_b32_e64 v97, v97, 0, s[80:81]
	v_cndmask_b32_e64 v98, v98, 0, s[78:79]
	v_cndmask_b32_e64 v99, v99, 0, s[76:77]
